# v35 + attn_combine ranges retuned (long-scan WGs 2 chunks, short-scan 19, short-carry 25, idle 28)
# speedup vs baseline: 1.0074x; 1.0074x over previous
; #define PREP(bit) for (int _r = 0; _r < (((PROBE2 >> (bit)) & 1) ? 2 : 1); ++_r)
; __device__ __forceinline__ int ltid(int wave) { int t = (wave << 6) | (int)__builtin_amdgcn_mbcnt_hi(~0u, __builtin_amdgcn_mbcnt_lo(~0u, 0u)); asm volatile("" : "+v"(t)); return t; }
; __device__ __forceinline__ int lbid() { int b = blockIdx.x; asm volatile("" : "+s"(b)); return b; }
; __device__ void attn_combine(const Params& p) {
;     ...
;     for (int e = lbid() * 512 + ltid(p.wave); e < MT * 64; e += gridDim.x * 512) {
;         const int tok = e >> 6, h = (e >> 3) & 7, c8 = e & 7;
;         const float l0 = LSE[(size_t)tok * 24 + h], l1 = LSE[(size_t)tok * 24 + 8 + h], l2 = LSE[(size_t)tok * 24 + 16 + h];
;         const float m = fmaxf(l0, fmaxf(l1, l2)); float w0 = __expf(l0 - m), w1 = __expf(l1 - m), w2 = __expf(l2 - m); const float inv = 1.0f / (w0 + w1 + w2); w0 *= inv; w1 *= inv; w2 *= inv;
; __global__ __launch_bounds__(512, 2) void mega(Params p0) {
;     ...
;             PREP(5) { lru_carry(p); s5_bscan(p, shm); attn_combine(p); }
.LBB0_256:
	s_mov_b32 s0, s80
	v_mov_b32_e32 v0, v60
	s_mov_b32 s1, 0x180000
	s_waitcnt lgkmcnt(0)
	s_lshl_b32 s2, s0, 1
	s_movk_i32 s3, 2
	s_cmpk_lt_i32 s0, 0x80
	s_cbranch_scc1 .Lcmb_set
	s_sub_i32 s2, s0, 0x80
	s_mul_i32 s2, s2, 19
	s_addk_i32 s2, 0x100
	s_movk_i32 s3, 19
	s_cmpk_lt_i32 s0, 0xc0
	s_cbranch_scc1 .Lcmb_set
	s_sub_i32 s2, s0, 0xc0
	s_mul_i32 s2, s2, 25
	s_addk_i32 s2, 0x5c0
	s_movk_i32 s3, 25
	s_cmpk_lt_i32 s0, 0xd0
	s_cbranch_scc1 .Lcmb_set
	s_sub_i32 s2, s0, 0xd0
	s_lshl_b32 s2, s2, 1
	s_addk_i32 s2, 0x750
	s_movk_i32 s3, 2
	s_cmpk_lt_i32 s0, 0xd4
	s_cbranch_scc1 .Lcmb_set
	s_sub_i32 s2, s0, 0xd4
	s_mul_i32 s2, s2, 28
	s_addk_i32 s2, 0x758
	s_movk_i32 s3, 28
